# instruction selection (lever 7): 100 v_mov_b32_dpp + v_fmac pairs in the ffn up-projection epilogue folded into v_fmac_f32_dpp, hazard pads re-derived
# speedup vs baseline: 1.0079x; 1.0079x over previous
; #define LAS __attribute__((address_space(3)))
;     __device__ __forceinline__ void operator()(const f32x4 (&acc)[2][2][4][2], const Unit& u, int wr, int wc, int fr, int fq) const {
;     ...
;                 const unsigned ob = (unsigned)((R0 + 64 * wr + frL) * DFF + f00) * 2u;
;                 f32x4 prevA = (f32x4){0.f, 0.f, 0.f, 0.f}, prevB = prevA;
; #pragma unroll
;                 for (int ai = 0; ai < 2; ++ai)
; #pragma unroll
;                     for (int m = 0; m < 4; ++m) {
;                         const int l = 128 * ai + 64 * wr + 16 * m + frL;
;                         const float rs = rt[l];
;                         if (m == 0) {
;                             const int B = 2 * ai + wr;
;                             prevA = (f32x4){0.f, 0.f, 0.f, 0.f}; prevB = prevA;
;                             if (B > 0 && frL >= 14) { const LAS float* hp = halo + ((B - 1) * 2 + (frL - 14)) * 128 + fl; prevA = *(const LAS f32x4*)hp; prevB = *(const LAS f32x4*)(hp + 4); }
;                         }
;                         unsigned wv[4];
; #pragma unroll
;                         for (int n = 0; n < 2; ++n) {
;                             const f32x4 w0 = n ? Wb0 : Wa0, w1 = n ? Wb1 : Wa1, w2 = n ? Wb2 : Wa2, bb = n ? Wbb : Wab;
;                             const f32x4 cur = acc[ai][1][m][n] * rs, uu = acc[ai][0][m][n] * rs, prev = n ? prevB : prevA;
;                             float ov[4];
; #pragma unroll
;                             for (int e = 0; e < 4; ++e) {
;                                 const float ce = cur[e], pe = prev[e];
;                                 const float g1 = dpp_mv<0x121>(k15 ? pe : ce), g2 = dpp_mv<0x122>(k14 ? pe : ce);
;                                 const float cv = fmaf(w0[e], g2, fmaf(w1[e], g1, fmaf(w2[e], ce, bb[e])));
;                                 ov[e] = siluf_(cv) * uu[e];
;                             }
;                             wv[2 * n] = cvt_pk_bf16(ov[0], ov[1]); wv[2 * n + 1] = cvt_pk_bf16(ov[2], ov[3]);
;                             if (n) prevB = cur; else prevA = cur;
;                         }
;                         if (ai > 0 || m > 0 || l >= 2) *(v4u*)((unsigned char*)ACT + (ob + (unsigned)((128 * ai + 16 * m) * DFF * 2))) = (v4u){wv[0], wv[1], wv[2], wv[3]};
;                         __builtin_amdgcn_sched_barrier(0);
;                     }
.LBB0_1391:
	s_or_b64 exec, exec, s[0:1]
	v_readlane_b32 s0, v255, 12
	s_add_i32 s0, s0, s21
	v_cmp_eq_u32_e64 s[6:7], 15, v212
	v_add_u32_e32 v2, s0, v212
	s_movk_i32 s0, 0xb00
	v_mul_lo_u32 v2, v2, s0
	s_waitcnt lgkmcnt(0)
	v_pk_mul_f32 v[128:129], v[128:129], v[0:1] op_sel_hi:[1,0]
	v_add_lshl_u32 v184, v184, v2, 1
	v_pk_mul_f32 v[2:3], v[130:131], v[0:1] op_sel_hi:[1,0]
	v_cndmask_b32_e64 v130, v128, v168, s[6:7]
	v_cndmask_b32_e32 v131, v168, v128, vcc
	s_waitcnt vmcnt(0)
	v_fma_f32 v168, v160, v128, v148
	v_fmac_f32_dpp v168, v130, v156 row_ror:1 row_mask:0xf bank_mask:0xf bound_ctrl:1
	v_fmac_f32_dpp v168, v131, v152 row_ror:2 row_mask:0xf bank_mask:0xf bound_ctrl:1
	v_mul_f32_e32 v130, 0xbfb8aa3b, v168
	v_exp_f32_e32 v130, v130
	v_mul_f32_e32 v124, v124, v0
	v_cndmask_b32_e32 v131, v169, v129, vcc
	v_mul_f32_e32 v125, v125, v0
	v_add_f32_e32 v130, 1.0, v130
	v_rcp_f32_e32 v130, v130
	v_mul_f32_e32 v126, v126, v0
	v_mul_f32_e32 v127, v127, v0
	v_mul_f32_e32 v130, v168, v130
	v_mul_f32_e32 v124, v124, v130
	v_cndmask_b32_e64 v130, v129, v169, s[6:7]
	v_fma_f32 v168, v161, v129, v149
	v_pk_mul_f32 v[120:121], v[120:121], v[0:1] op_sel_hi:[1,0]
	v_fmac_f32_dpp v168, v130, v157 row_ror:1 row_mask:0xf bank_mask:0xf bound_ctrl:1
	v_fmac_f32_dpp v168, v131, v153 row_ror:2 row_mask:0xf bank_mask:0xf bound_ctrl:1
	v_mul_f32_e32 v130, 0xbfb8aa3b, v168
	v_exp_f32_e32 v130, v130
	v_cndmask_b32_e32 v131, v170, v2, vcc
	v_mul_f32_e32 v116, v116, v0
	v_pk_mul_f32 v[122:123], v[122:123], v[0:1] op_sel_hi:[1,0]
	v_add_f32_e32 v130, 1.0, v130
	v_rcp_f32_e32 v130, v130
	v_mul_f32_e32 v117, v117, v0
	v_mul_f32_e32 v118, v118, v0
	v_mul_f32_e32 v130, v168, v130
	v_mul_f32_e32 v125, v125, v130
	v_cndmask_b32_e64 v130, v2, v170, s[6:7]
	v_fma_f32 v168, v162, v2, v150
	v_cvt_pk_bf16_f32 v124, v124, v125
	v_mul_f32_e32 v0, v119, v0
	v_fmac_f32_dpp v168, v130, v158 row_ror:1 row_mask:0xf bank_mask:0xf bound_ctrl:1
	v_fmac_f32_dpp v168, v131, v154 row_ror:2 row_mask:0xf bank_mask:0xf bound_ctrl:1
	v_mul_f32_e32 v130, 0xbfb8aa3b, v168
	v_exp_f32_e32 v130, v130
	v_cndmask_b32_e32 v131, v171, v3, vcc
	v_cmp_lt_i32_e64 s[0:1], 1, v211
	v_add_f32_e32 v130, 1.0, v130
	v_rcp_f32_e32 v130, v130
	v_mov_b32_dpp v131, v131 row_ror:2 row_mask:0xf bank_mask:0xf bound_ctrl:1
	v_mul_f32_e32 v130, v168, v130
	v_mul_f32_e32 v126, v126, v130
	v_cndmask_b32_e64 v130, v3, v171, s[6:7]
	v_fma_f32 v168, v163, v3, v151
	s_nop 0
	v_fmac_f32_dpp v168, v130, v159 row_ror:1 row_mask:0xf bank_mask:0xf bound_ctrl:1
	v_fmac_f32_e32 v168, v155, v131
	v_mul_f32_e32 v130, 0xbfb8aa3b, v168
	v_exp_f32_e32 v130, v130
	s_nop 0
	v_add_f32_e32 v130, 1.0, v130
	v_rcp_f32_e32 v130, v130
	s_nop 0
	v_mul_f32_e32 v130, v168, v130
	v_mul_f32_e32 v127, v127, v130
	v_cvt_pk_bf16_f32 v125, v126, v127
	v_cndmask_b32_e64 v126, v120, v164, s[6:7]
	v_cndmask_b32_e32 v127, v164, v120, vcc
	v_fma_f32 v130, v144, v120, v132
	v_fmac_f32_dpp v130, v126, v140 row_ror:1 row_mask:0xf bank_mask:0xf bound_ctrl:1
	v_fmac_f32_dpp v130, v127, v136 row_ror:2 row_mask:0xf bank_mask:0xf bound_ctrl:1
	v_mul_f32_e32 v126, 0xbfb8aa3b, v130
	v_exp_f32_e32 v126, v126
	v_cndmask_b32_e32 v127, v165, v121, vcc
	v_add_f32_e32 v126, 1.0, v126
	v_rcp_f32_e32 v126, v126
	s_nop 0
	v_mul_f32_e32 v126, v130, v126
	v_mul_f32_e32 v116, v116, v126
	v_cndmask_b32_e64 v126, v121, v165, s[6:7]
	v_fma_f32 v130, v145, v121, v133
	s_nop 0
	v_fmac_f32_dpp v130, v126, v141 row_ror:1 row_mask:0xf bank_mask:0xf bound_ctrl:1
	v_fmac_f32_dpp v130, v127, v137 row_ror:2 row_mask:0xf bank_mask:0xf bound_ctrl:1
	v_mul_f32_e32 v126, 0xbfb8aa3b, v130
	v_exp_f32_e32 v126, v126
	v_cndmask_b32_e32 v127, v166, v122, vcc
	v_add_f32_e32 v126, 1.0, v126
	v_rcp_f32_e32 v126, v126
	s_nop 0
	v_mul_f32_e32 v126, v130, v126
	v_mul_f32_e32 v117, v117, v126
	v_cndmask_b32_e64 v126, v122, v166, s[6:7]
	v_fma_f32 v130, v146, v122, v134
	s_nop 0
	v_fmac_f32_dpp v130, v126, v142 row_ror:1 row_mask:0xf bank_mask:0xf bound_ctrl:1
	v_fmac_f32_dpp v130, v127, v138 row_ror:2 row_mask:0xf bank_mask:0xf bound_ctrl:1
	v_mul_f32_e32 v126, 0xbfb8aa3b, v130
	v_exp_f32_e32 v126, v126
	v_cndmask_b32_e32 v127, v167, v123, vcc
	v_add_f32_e32 v126, 1.0, v126
	v_rcp_f32_e32 v126, v126
	s_nop 0
	v_mul_f32_e32 v126, v130, v126
	v_mul_f32_e32 v118, v118, v126
	v_cndmask_b32_e64 v126, v123, v167, s[6:7]
	v_fma_f32 v130, v147, v123, v135
	s_nop 0
	v_fmac_f32_dpp v130, v126, v143 row_ror:1 row_mask:0xf bank_mask:0xf bound_ctrl:1
	v_fmac_f32_dpp v130, v127, v139 row_ror:2 row_mask:0xf bank_mask:0xf bound_ctrl:1
	v_mul_f32_e32 v126, 0xbfb8aa3b, v130
	v_exp_f32_e32 v126, v126
	s_nop 0
	v_add_f32_e32 v126, 1.0, v126
	v_rcp_f32_e32 v126, v126
	s_nop 0
	v_mul_f32_e32 v126, v130, v126
	v_mul_f32_e32 v0, v0, v126
	v_cvt_pk_bf16_f32 v126, v116, v117
	v_cvt_pk_bf16_f32 v127, v118, v0
	s_and_saveexec_b64 s[8:9], s[0:1]
	s_cbranch_execz .LBB0_1393
	v_readlane_b32 s0, v252, 8
	v_readlane_b32 s1, v252, 9
	s_nop 4
	global_store_dwordx4 v184, v[124:127], s[0:1]
; #define LAS __attribute__((address_space(3)))
; __device__ __forceinline__ unsigned cvt_pk_bf16(float lo, float hi) { unsigned r; asm("v_cvt_pk_bf16_f32 %0, %1, %2" : "=v"(r) : "v"(lo), "v"(hi)); return r; }
; __device__ __forceinline__ float siluf_(float x) { return x * rcpf_(1.f + __expf(-x)); }
;     __device__ __forceinline__ void operator()(const f32x4 (&acc)[2][2][4][2], const Unit& u, int wr, int wc, int fr, int fq) const {
;     ...
;                     for (int m = 0; m < 4; ++m) {
;                         const int l = 128 * ai + 64 * wr + 16 * m + frL;
;                         const float rs = rt[l];
;                         if (m == 0) {
;                             const int B = 2 * ai + wr;
;                             prevA = (f32x4){0.f, 0.f, 0.f, 0.f}; prevB = prevA;
;                             if (B > 0 && frL >= 14) { const LAS float* hp = halo + ((B - 1) * 2 + (frL - 14)) * 128 + fl; prevA = *(const LAS f32x4*)hp; prevB = *(const LAS f32x4*)(hp + 4); }
;                         }
;                         unsigned wv[4];
; #pragma unroll
;                         for (int n = 0; n < 2; ++n) {
;                             const f32x4 w0 = n ? Wb0 : Wa0, w1 = n ? Wb1 : Wa1, w2 = n ? Wb2 : Wa2, bb = n ? Wbb : Wab;
;                             const f32x4 cur = acc[ai][1][m][n] * rs, uu = acc[ai][0][m][n] * rs, prev = n ? prevB : prevA;
;                             float ov[4];
; #pragma unroll
;                             for (int e = 0; e < 4; ++e) {
;                                 const float ce = cur[e], pe = prev[e];
;                                 const float g1 = dpp_mv<0x121>(k15 ? pe : ce), g2 = dpp_mv<0x122>(k14 ? pe : ce);
;                                 const float cv = fmaf(w0[e], g2, fmaf(w1[e], g1, fmaf(w2[e], ce, bb[e])));
;                                 ov[e] = siluf_(cv) * uu[e];
;                             }
;                             wv[2 * n] = cvt_pk_bf16(ov[0], ov[1]); wv[2 * n + 1] = cvt_pk_bf16(ov[2], ov[3]);
;                             if (n) prevB = cur; else prevA = cur;
;                         }
;                         if (ai > 0 || m > 0 || l >= 2) *(v4u*)((unsigned char*)ACT + (ob + (unsigned)((128 * ai + 16 * m) * DFF * 2))) = (v4u){wv[0], wv[1], wv[2], wv[3]};
;                         __builtin_amdgcn_sched_barrier(0);
;                     }
.LBB0_1393:
	s_or_b64 exec, exec, s[8:9]
	ds_read_b32 v116, v209 offset:64
	v_mov_b32_e32 v118, v108
	v_readlane_b32 s0, v252, 8
	v_readlane_b32 s1, v252, 9
	s_waitcnt lgkmcnt(0)
	v_pk_mul_f32 v[112:113], v[112:113], v[116:117] op_sel_hi:[1,0]
	s_nop 0
	v_cndmask_b32_e64 v0, v112, v128, s[6:7]
	v_pk_mul_f32 v[114:115], v[114:115], v[116:117] op_sel_hi:[1,0]
	v_cndmask_b32_e32 v117, v128, v112, vcc
	v_fma_f32 v119, v160, v112, v148
	v_fmac_f32_dpp v119, v0, v156 row_ror:1 row_mask:0xf bank_mask:0xf bound_ctrl:1
	v_fmac_f32_dpp v119, v117, v152 row_ror:2 row_mask:0xf bank_mask:0xf bound_ctrl:1
	v_mul_f32_e32 v0, 0xbfb8aa3b, v119
	v_exp_f32_e32 v0, v0
	v_cndmask_b32_e64 v108, v113, v129, s[6:7]
	v_add_f32_e32 v0, 1.0, v0
	v_rcp_f32_e32 v117, v0
	s_nop 0
	v_pk_mul_f32 v[118:119], v[118:119], v[116:117]
	s_nop 0
	v_mul_f32_e32 v0, v118, v119
	v_cndmask_b32_e32 v117, v129, v113, vcc
	v_fma_f32 v119, v161, v113, v149
	v_fmac_f32_dpp v119, v108, v157 row_ror:1 row_mask:0xf bank_mask:0xf bound_ctrl:1
	v_fmac_f32_dpp v119, v117, v153 row_ror:2 row_mask:0xf bank_mask:0xf bound_ctrl:1
	v_mul_f32_e32 v108, 0xbfb8aa3b, v119
	v_exp_f32_e32 v108, v108
	v_mov_b32_e32 v118, v109
	v_add_f32_e32 v108, 1.0, v108
	v_rcp_f32_e32 v117, v108
	s_nop 0
	v_pk_mul_f32 v[108:109], v[118:119], v[116:117]
	s_nop 0
	v_mul_f32_e32 v118, v108, v109
	v_cndmask_b32_e64 v108, v114, v2, s[6:7]
	v_cndmask_b32_e32 v2, v2, v114, vcc
	v_fma_f32 v109, v162, v114, v150
	v_fmac_f32_dpp v109, v108, v158 row_ror:1 row_mask:0xf bank_mask:0xf bound_ctrl:1
	v_fmac_f32_dpp v109, v2, v154 row_ror:2 row_mask:0xf bank_mask:0xf bound_ctrl:1
	v_mul_f32_e32 v2, 0xbfb8aa3b, v109
	v_exp_f32_e32 v2, v2
	v_mov_b32_e32 v108, v110
	v_add_f32_e32 v2, 1.0, v2
	v_rcp_f32_e32 v117, v2
	v_cndmask_b32_e64 v2, v115, v3, s[6:7]
	v_cndmask_b32_e32 v3, v3, v115, vcc
	v_pk_mul_f32 v[108:109], v[108:109], v[116:117]
	s_nop 0
	v_mul_f32_e32 v109, v108, v109
	v_mov_b32_dpp v108, v3 row_ror:2 row_mask:0xf bank_mask:0xf bound_ctrl:1
	v_fma_f32 v3, v163, v115, v151
	v_fmac_f32_dpp v3, v2, v159 row_ror:1 row_mask:0xf bank_mask:0xf bound_ctrl:1
	v_fmac_f32_e32 v3, v155, v108
	v_mul_f32_e32 v2, 0xbfb8aa3b, v3
	v_exp_f32_e32 v2, v2
	v_cvt_pk_bf16_f32 v108, v0, v118
	s_nop 0
	v_add_f32_e32 v2, 1.0, v2
	v_rcp_f32_e32 v117, v2
	v_mov_b32_e32 v2, v111
	v_pk_mul_f32 v[2:3], v[2:3], v[116:117]
	v_pk_mul_f32 v[104:105], v[104:105], v[116:117] op_sel_hi:[1,0]
	v_mul_f32_e32 v2, v2, v3
	v_cndmask_b32_e64 v0, v104, v120, s[6:7]
	v_cvt_pk_bf16_f32 v109, v109, v2
	v_pk_mul_f32 v[2:3], v[106:107], v[116:117] op_sel_hi:[1,0]
	v_cndmask_b32_e32 v106, v120, v104, vcc
	v_fma_f32 v107, v144, v104, v132
	v_fmac_f32_dpp v107, v0, v140 row_ror:1 row_mask:0xf bank_mask:0xf bound_ctrl:1
	v_fmac_f32_dpp v107, v106, v136 row_ror:2 row_mask:0xf bank_mask:0xf bound_ctrl:1
	v_mul_f32_e32 v0, 0xbfb8aa3b, v107
	v_exp_f32_e32 v0, v0
	v_mov_b32_e32 v106, v100
	v_cndmask_b32_e64 v100, v105, v121, s[6:7]
	v_add_f32_e32 v0, 1.0, v0
	v_rcp_f32_e32 v117, v0
	s_nop 0
	v_pk_mul_f32 v[106:107], v[106:107], v[116:117]
	s_nop 0
	v_mul_f32_e32 v0, v106, v107
	v_cndmask_b32_e32 v106, v121, v105, vcc
	v_fma_f32 v107, v145, v105, v133
	v_fmac_f32_dpp v107, v100, v141 row_ror:1 row_mask:0xf bank_mask:0xf bound_ctrl:1
	v_fmac_f32_dpp v107, v106, v137 row_ror:2 row_mask:0xf bank_mask:0xf bound_ctrl:1
	v_mul_f32_e32 v100, 0xbfb8aa3b, v107
	v_exp_f32_e32 v100, v100
	v_mov_b32_e32 v106, v101
	v_add_f32_e32 v100, 1.0, v100
	v_rcp_f32_e32 v117, v100
	s_nop 0
	v_pk_mul_f32 v[100:101], v[106:107], v[116:117]
	s_nop 0
	v_mul_f32_e32 v106, v100, v101
	v_cndmask_b32_e64 v100, v2, v122, s[6:7]
	v_cndmask_b32_e32 v101, v122, v2, vcc
	v_cvt_pk_bf16_f32 v110, v0, v106
	v_add_u32_e32 v0, 0x16000, v184
	v_mov_b32_dpp v107, v101 row_ror:2 row_mask:0xf bank_mask:0xf bound_ctrl:1
	v_fma_f32 v101, v146, v2, v134
	v_fmac_f32_dpp v101, v100, v142 row_ror:1 row_mask:0xf bank_mask:0xf bound_ctrl:1
	v_fmac_f32_e32 v101, v138, v107
	v_mul_f32_e32 v100, 0xbfb8aa3b, v101
	v_exp_f32_e32 v100, v100
	s_nop 0
	v_add_f32_e32 v100, 1.0, v100
	v_rcp_f32_e32 v117, v100
	v_mov_b32_e32 v100, v102
	v_pk_mul_f32 v[100:101], v[100:101], v[116:117]
	s_nop 0
	v_mul_f32_e32 v102, v100, v101
	v_cndmask_b32_e64 v100, v3, v123, s[6:7]
	v_cndmask_b32_e32 v101, v123, v3, vcc
	s_nop 0
	s_nop 0
	v_mov_b32_dpp v107, v101 row_ror:2 row_mask:0xf bank_mask:0xf bound_ctrl:1
	v_fma_f32 v101, v147, v3, v135
	v_fmac_f32_dpp v101, v100, v143 row_ror:1 row_mask:0xf bank_mask:0xf bound_ctrl:1
	v_fmac_f32_e32 v101, v139, v107
	v_mul_f32_e32 v100, 0xbfb8aa3b, v101
	v_exp_f32_e32 v100, v100
	s_nop 0
	v_add_f32_e32 v100, 1.0, v100
	v_rcp_f32_e32 v117, v100
	v_mov_b32_e32 v100, v103
	v_pk_mul_f32 v[100:101], v[100:101], v[116:117]
	s_nop 0
	v_mul_f32_e32 v100, v100, v101
	v_cvt_pk_bf16_f32 v111, v102, v100
	global_store_dwordx4 v0, v[108:111], s[0:1]
	ds_read_b32 v100, v209 offset:128
	v_mov_b32_e32 v102, v92
	s_waitcnt lgkmcnt(0)
; #define LAS __attribute__((address_space(3)))
; __device__ __forceinline__ unsigned cvt_pk_bf16(float lo, float hi) { unsigned r; asm("v_cvt_pk_bf16_f32 %0, %1, %2" : "=v"(r) : "v"(lo), "v"(hi)); return r; }
; __device__ __forceinline__ float siluf_(float x) { return x * rcpf_(1.f + __expf(-x)); }
;     __device__ __forceinline__ void operator()(const f32x4 (&acc)[2][2][4][2], const Unit& u, int wr, int wc, int fr, int fq) const {
;     ...
;                     for (int m = 0; m < 4; ++m) {
;                         const int l = 128 * ai + 64 * wr + 16 * m + frL;
;                         const float rs = rt[l];
;                         if (m == 0) {
;                             const int B = 2 * ai + wr;
;                             prevA = (f32x4){0.f, 0.f, 0.f, 0.f}; prevB = prevA;
;                             if (B > 0 && frL >= 14) { const LAS float* hp = halo + ((B - 1) * 2 + (frL - 14)) * 128 + fl; prevA = *(const LAS f32x4*)hp; prevB = *(const LAS f32x4*)(hp + 4); }
;                         }
;                         unsigned wv[4];
; #pragma unroll
;                         for (int n = 0; n < 2; ++n) {
;                             const f32x4 w0 = n ? Wb0 : Wa0, w1 = n ? Wb1 : Wa1, w2 = n ? Wb2 : Wa2, bb = n ? Wbb : Wab;
;                             const f32x4 cur = acc[ai][1][m][n] * rs, uu = acc[ai][0][m][n] * rs, prev = n ? prevB : prevA;
;                             float ov[4];
; #pragma unroll
;                             for (int e = 0; e < 4; ++e) {
;                                 const float ce = cur[e], pe = prev[e];
;                                 const float g1 = dpp_mv<0x121>(k15 ? pe : ce), g2 = dpp_mv<0x122>(k14 ? pe : ce);
;                                 const float cv = fmaf(w0[e], g2, fmaf(w1[e], g1, fmaf(w2[e], ce, bb[e])));
;                                 ov[e] = siluf_(cv) * uu[e];
;                             }
;                             wv[2 * n] = cvt_pk_bf16(ov[0], ov[1]); wv[2 * n + 1] = cvt_pk_bf16(ov[2], ov[3]);
;                             if (n) prevB = cur; else prevA = cur;
;                         }
;                         if (ai > 0 || m > 0 || l >= 2) *(v4u*)((unsigned char*)ACT + (ob + (unsigned)((128 * ai + 16 * m) * DFF * 2))) = (v4u){wv[0], wv[1], wv[2], wv[3]};
;                         __builtin_amdgcn_sched_barrier(0);
;                     }
	v_pk_mul_f32 v[96:97], v[96:97], v[100:101] op_sel_hi:[1,0]
	s_nop 0
	v_cndmask_b32_e64 v0, v96, v112, s[6:7]
	v_pk_mul_f32 v[98:99], v[98:99], v[100:101] op_sel_hi:[1,0]
	v_cndmask_b32_e32 v101, v112, v96, vcc
	v_fma_f32 v103, v160, v96, v148
	v_fmac_f32_dpp v103, v0, v156 row_ror:1 row_mask:0xf bank_mask:0xf bound_ctrl:1
	v_fmac_f32_dpp v103, v101, v152 row_ror:2 row_mask:0xf bank_mask:0xf bound_ctrl:1
	v_mul_f32_e32 v0, 0xbfb8aa3b, v103
	v_exp_f32_e32 v0, v0
	v_cndmask_b32_e64 v92, v97, v113, s[6:7]
	v_add_f32_e32 v0, 1.0, v0
	v_rcp_f32_e32 v101, v0
	s_nop 0
	v_pk_mul_f32 v[102:103], v[102:103], v[100:101]
	s_nop 0
	v_mul_f32_e32 v0, v102, v103
	v_cndmask_b32_e32 v101, v113, v97, vcc
	v_fma_f32 v103, v161, v97, v149
	v_fmac_f32_dpp v103, v92, v157 row_ror:1 row_mask:0xf bank_mask:0xf bound_ctrl:1
	v_fmac_f32_dpp v103, v101, v153 row_ror:2 row_mask:0xf bank_mask:0xf bound_ctrl:1
	v_mul_f32_e32 v92, 0xbfb8aa3b, v103
	v_exp_f32_e32 v92, v92
	v_mov_b32_e32 v102, v93
	v_add_f32_e32 v92, 1.0, v92
	v_rcp_f32_e32 v101, v92
	s_nop 0
	v_pk_mul_f32 v[92:93], v[102:103], v[100:101]
	s_nop 0
	v_mul_f32_e32 v102, v92, v93
	v_cndmask_b32_e64 v92, v98, v114, s[6:7]
	v_cndmask_b32_e32 v93, v114, v98, vcc
	s_nop 0
	s_nop 0
	v_mov_b32_dpp v101, v93 row_ror:2 row_mask:0xf bank_mask:0xf bound_ctrl:1
	v_fma_f32 v93, v162, v98, v150
	v_fmac_f32_dpp v93, v92, v158 row_ror:1 row_mask:0xf bank_mask:0xf bound_ctrl:1
	v_fmac_f32_e32 v93, v154, v101
	v_mul_f32_e32 v92, 0xbfb8aa3b, v93
	v_exp_f32_e32 v92, v92
	s_nop 0
	v_add_f32_e32 v92, 1.0, v92
	v_rcp_f32_e32 v101, v92
	v_mov_b32_e32 v92, v94
	v_pk_mul_f32 v[92:93], v[92:93], v[100:101]
	s_nop 0
	v_mul_f32_e32 v94, v92, v93
	v_cndmask_b32_e64 v92, v99, v115, s[6:7]
	v_cndmask_b32_e32 v93, v115, v99, vcc
	s_nop 0
	s_nop 0
	v_mov_b32_dpp v101, v93 row_ror:2 row_mask:0xf bank_mask:0xf bound_ctrl:1
	v_fma_f32 v93, v163, v99, v151
	v_fmac_f32_dpp v93, v92, v159 row_ror:1 row_mask:0xf bank_mask:0xf bound_ctrl:1
	v_fmac_f32_e32 v93, v155, v101
	v_mul_f32_e32 v92, 0xbfb8aa3b, v93
	v_exp_f32_e32 v92, v92
	s_nop 0
	v_add_f32_e32 v92, 1.0, v92
	v_rcp_f32_e32 v101, v92
	v_mov_b32_e32 v92, v95
	v_pk_mul_f32 v[92:93], v[92:93], v[100:101]
	v_pk_mul_f32 v[88:89], v[88:89], v[100:101] op_sel_hi:[1,0]
	v_mul_f32_e32 v93, v92, v93
	v_cvt_pk_bf16_f32 v92, v0, v102
	v_cndmask_b32_e64 v0, v88, v104, s[6:7]
	v_cvt_pk_bf16_f32 v93, v94, v93
	v_cndmask_b32_e32 v94, v104, v88, vcc
	v_fma_f32 v95, v144, v88, v132
	v_fmac_f32_dpp v95, v0, v140 row_ror:1 row_mask:0xf bank_mask:0xf bound_ctrl:1
	v_fmac_f32_dpp v95, v94, v136 row_ror:2 row_mask:0xf bank_mask:0xf bound_ctrl:1
	v_mul_f32_e32 v0, 0xbfb8aa3b, v95
	v_exp_f32_e32 v0, v0
	v_pk_mul_f32 v[90:91], v[90:91], v[100:101] op_sel_hi:[1,0]
	v_mov_b32_e32 v94, v84
	v_cndmask_b32_e64 v84, v89, v105, s[6:7]
	v_add_f32_e32 v0, 1.0, v0
	v_rcp_f32_e32 v101, v0
	s_nop 0
	v_pk_mul_f32 v[94:95], v[94:95], v[100:101]
	s_nop 0
	v_mul_f32_e32 v0, v94, v95
	v_cndmask_b32_e32 v94, v105, v89, vcc
	v_fma_f32 v95, v145, v89, v133
	v_fmac_f32_dpp v95, v84, v141 row_ror:1 row_mask:0xf bank_mask:0xf bound_ctrl:1
	v_fmac_f32_dpp v95, v94, v137 row_ror:2 row_mask:0xf bank_mask:0xf bound_ctrl:1
	v_mul_f32_e32 v84, 0xbfb8aa3b, v95
	v_exp_f32_e32 v84, v84
	v_mov_b32_e32 v94, v85
	v_add_f32_e32 v84, 1.0, v84
	v_rcp_f32_e32 v101, v84
	s_nop 0
	v_pk_mul_f32 v[84:85], v[94:95], v[100:101]
	s_nop 0
	v_mul_f32_e32 v94, v84, v85
	v_cndmask_b32_e64 v84, v90, v2, s[6:7]
	v_cndmask_b32_e32 v2, v2, v90, vcc
	v_fma_f32 v85, v146, v90, v134
	v_fmac_f32_dpp v85, v84, v142 row_ror:1 row_mask:0xf bank_mask:0xf bound_ctrl:1
	v_fmac_f32_dpp v85, v2, v138 row_ror:2 row_mask:0xf bank_mask:0xf bound_ctrl:1
	v_mul_f32_e32 v2, 0xbfb8aa3b, v85
	v_exp_f32_e32 v2, v2
	v_mov_b32_e32 v84, v86
	v_cvt_pk_bf16_f32 v94, v0, v94
	v_add_u32_e32 v0, 0x2c000, v184
	v_add_f32_e32 v2, 1.0, v2
	v_rcp_f32_e32 v101, v2
	v_cndmask_b32_e64 v2, v91, v3, s[6:7]
	v_cndmask_b32_e32 v3, v3, v91, vcc
	v_pk_mul_f32 v[84:85], v[84:85], v[100:101]
	s_nop 0
	v_mul_f32_e32 v84, v84, v85
	v_mov_b32_dpp v85, v3 row_ror:2 row_mask:0xf bank_mask:0xf bound_ctrl:1
	v_fma_f32 v3, v147, v91, v135
	v_fmac_f32_dpp v3, v2, v143 row_ror:1 row_mask:0xf bank_mask:0xf bound_ctrl:1
	v_fmac_f32_e32 v3, v139, v85
	v_mul_f32_e32 v2, 0xbfb8aa3b, v3
	v_exp_f32_e32 v2, v2
	s_nop 0
	v_add_f32_e32 v2, 1.0, v2
	v_rcp_f32_e32 v101, v2
	v_mov_b32_e32 v2, v87
	v_pk_mul_f32 v[2:3], v[2:3], v[100:101]
	s_nop 0
	v_mul_f32_e32 v2, v2, v3
	v_cvt_pk_bf16_f32 v95, v84, v2
	global_store_dwordx4 v0, v[92:95], s[0:1]
	ds_read_b32 v2, v209 offset:192
	v_mov_b32_e32 v86, v78
	s_waitcnt lgkmcnt(0)
; #define LAS __attribute__((address_space(3)))
;     __device__ __forceinline__ void operator()(const f32x4 (&acc)[2][2][4][2], const Unit& u, int wr, int wc, int fr, int fq) const {
;     ...
;                     for (int m = 0; m < 4; ++m) {
;                         const int l = 128 * ai + 64 * wr + 16 * m + frL;
;                         const float rs = rt[l];
;                         if (m == 0) {
;                             const int B = 2 * ai + wr;
;                             prevA = (f32x4){0.f, 0.f, 0.f, 0.f}; prevB = prevA;
;                             if (B > 0 && frL >= 14) { const LAS float* hp = halo + ((B - 1) * 2 + (frL - 14)) * 128 + fl; prevA = *(const LAS f32x4*)hp; prevB = *(const LAS f32x4*)(hp + 4); }
;                         }
	v_pk_mul_f32 v[80:81], v[80:81], v[2:3] op_sel_hi:[1,0]
	s_nop 0
	v_cndmask_b32_e64 v0, v80, v96, s[6:7]
	v_pk_mul_f32 v[82:83], v[82:83], v[2:3] op_sel_hi:[1,0]
	v_cndmask_b32_e32 v3, v96, v80, vcc
	v_fma_f32 v85, v160, v80, v148
	v_fmac_f32_dpp v85, v0, v156 row_ror:1 row_mask:0xf bank_mask:0xf bound_ctrl:1
	v_fmac_f32_dpp v85, v3, v152 row_ror:2 row_mask:0xf bank_mask:0xf bound_ctrl:1
	v_mul_f32_e32 v0, 0xbfb8aa3b, v85
	v_exp_f32_e32 v0, v0
	v_cndmask_b32_e64 v3, v81, v97, s[6:7]
	v_cndmask_b32_e32 v80, v97, v81, vcc
	v_fma_f32 v81, v161, v81, v149
	v_mov_b32_dpp v84, v3 row_ror:1 row_mask:0xf bank_mask:0xf bound_ctrl:1
	v_add_f32_e32 v0, 1.0, v0
	v_rcp_f32_e32 v3, v0
	v_fmac_f32_e32 v81, v157, v84
	v_mov_b32_dpp v0, v80 row_ror:2 row_mask:0xf bank_mask:0xf bound_ctrl:1
	v_fmac_f32_e32 v81, v153, v0
	v_mul_f32_e32 v0, 0xbfb8aa3b, v81
	v_exp_f32_e32 v0, v0
	v_mov_b32_e32 v84, v76
	v_pk_mul_f32 v[84:85], v[84:85], v[2:3]
	v_cndmask_b32_e32 v76, v98, v82, vcc
	v_add_f32_e32 v0, 1.0, v0
	v_rcp_f32_e32 v3, v0
	v_cndmask_b32_e64 v0, v82, v98, s[6:7]
	v_fma_f32 v87, v162, v82, v150
	v_mov_b32_dpp v76, v76 row_ror:2 row_mask:0xf bank_mask:0xf bound_ctrl:1
	v_fmac_f32_dpp v87, v0, v158 row_ror:1 row_mask:0xf bank_mask:0xf bound_ctrl:1
	v_fmac_f32_e32 v87, v154, v76
	v_mul_f32_e32 v0, 0xbfb8aa3b, v87
	v_exp_f32_e32 v0, v0
	v_mov_b32_e32 v80, v77
	v_pk_mul_f32 v[76:77], v[80:81], v[2:3]
	v_cndmask_b32_e32 v80, v99, v83, vcc
	v_add_f32_e32 v0, 1.0, v0
	v_rcp_f32_e32 v3, v0
	v_cndmask_b32_e64 v0, v83, v99, s[6:7]
	v_fma_f32 v81, v163, v83, v151
	s_nop 0
	v_fmac_f32_dpp v81, v0, v159 row_ror:1 row_mask:0xf bank_mask:0xf bound_ctrl:1
	v_fmac_f32_dpp v81, v80, v155 row_ror:2 row_mask:0xf bank_mask:0xf bound_ctrl:1
	v_mul_f32_e32 v0, 0xbfb8aa3b, v81
	v_exp_f32_e32 v0, v0
	v_pk_mul_f32 v[82:83], v[86:87], v[2:3]
	v_mov_b32_e32 v80, v79
	v_mul_f32_e32 v84, v84, v85
	v_add_f32_e32 v0, 1.0, v0
	v_rcp_f32_e32 v3, v0
	v_mul_f32_e32 v0, v76, v77
	v_mul_f32_e32 v82, v82, v83
	v_pk_mul_f32 v[72:73], v[72:73], v[2:3] op_sel_hi:[1,0]
	s_nop 0
	v_cndmask_b32_e64 v76, v72, v88, s[6:7]
	v_cndmask_b32_e32 v77, v88, v72, vcc
	v_pk_mul_f32 v[74:75], v[74:75], v[2:3] op_sel_hi:[1,0]
	s_nop 0
	v_mov_b32_dpp v78, v77 row_ror:2 row_mask:0xf bank_mask:0xf bound_ctrl:1
	v_fma_f32 v77, v144, v72, v132
	v_fmac_f32_dpp v77, v76, v140 row_ror:1 row_mask:0xf bank_mask:0xf bound_ctrl:1
	v_fmac_f32_e32 v77, v136, v78
	v_mul_f32_e32 v72, 0xbfb8aa3b, v77
	v_exp_f32_e32 v72, v72
	v_pk_mul_f32 v[78:79], v[80:81], v[2:3]
	v_cndmask_b32_e32 v76, v89, v73, vcc
	v_mul_f32_e32 v78, v78, v79
	v_add_f32_e32 v3, 1.0, v72
	v_cndmask_b32_e64 v72, v73, v89, s[6:7]
	v_fma_f32 v79, v145, v73, v133
	s_nop 0
	v_fmac_f32_dpp v79, v72, v141 row_ror:1 row_mask:0xf bank_mask:0xf bound_ctrl:1
	v_fmac_f32_dpp v79, v76, v137 row_ror:2 row_mask:0xf bank_mask:0xf bound_ctrl:1
	v_mul_f32_e32 v72, 0xbfb8aa3b, v79
	v_exp_f32_e32 v73, v72
	v_rcp_f32_e32 v3, v3
	v_cvt_pk_bf16_f32 v72, v84, v0
	v_mov_b32_e32 v76, v68
	v_add_f32_e32 v0, 1.0, v73
	v_pk_mul_f32 v[76:77], v[76:77], v[2:3]
	v_rcp_f32_e32 v3, v0
	v_cndmask_b32_e64 v0, v74, v90, s[6:7]
	v_cndmask_b32_e32 v68, v90, v74, vcc
	v_fma_f32 v81, v146, v74, v134
	s_nop 0
	v_mov_b32_dpp v68, v68 row_ror:2 row_mask:0xf bank_mask:0xf bound_ctrl:1
	v_fmac_f32_dpp v81, v0, v142 row_ror:1 row_mask:0xf bank_mask:0xf bound_ctrl:1
	v_fmac_f32_e32 v81, v138, v68
	v_mul_f32_e32 v0, 0xbfb8aa3b, v81
	v_exp_f32_e32 v0, v0
	v_cvt_pk_bf16_f32 v73, v82, v78
	v_mov_b32_e32 v78, v69
	v_pk_mul_f32 v[68:69], v[78:79], v[2:3]
	v_add_f32_e32 v0, 1.0, v0
	v_rcp_f32_e32 v3, v0
	v_cndmask_b32_e64 v0, v75, v91, s[6:7]
	v_cndmask_b32_e32 v74, v91, v75, vcc
	v_fma_f32 v75, v147, v75, v135
	v_fmac_f32_dpp v75, v0, v143 row_ror:1 row_mask:0xf bank_mask:0xf bound_ctrl:1
	v_fmac_f32_dpp v75, v74, v139 row_ror:2 row_mask:0xf bank_mask:0xf bound_ctrl:1
	v_mul_f32_e32 v0, 0xbfb8aa3b, v75
	v_exp_f32_e32 v0, v0
	v_mov_b32_e32 v80, v70
	v_mul_f32_e32 v78, v76, v77
	v_pk_mul_f32 v[76:77], v[80:81], v[2:3]
	v_add_f32_e32 v0, 1.0, v0
	v_rcp_f32_e32 v3, v0
	v_mul_f32_e32 v0, v68, v69
	v_mov_b32_e32 v74, v71
	v_mul_f32_e32 v68, v76, v77
	v_pk_mul_f32 v[2:3], v[74:75], v[2:3]
	v_cvt_pk_bf16_f32 v74, v78, v0
	v_add_u32_e32 v0, 0x42000, v184
	v_mul_f32_e32 v2, v2, v3
	v_cvt_pk_bf16_f32 v75, v68, v2
	global_store_dwordx4 v0, v[72:75], s[0:1]
	ds_read_b32 v76, v209 offset:512
	s_nor_b64 s[8:9], s[30:31], vcc
	v_mov_b32_e32 v68, 0
	v_mov_b32_e32 v69, 0
	v_mov_b32_e32 v70, 0
	v_mov_b32_e32 v71, 0
	v_mov_b32_e32 v72, 0
	v_mov_b32_e32 v73, 0
	v_mov_b32_e32 v74, 0
	v_mov_b32_e32 v75, 0
	s_and_saveexec_b64 s[0:1], s[8:9]
	s_cbranch_execz .LBB0_1395
	s_movk_i32 s8, 0xe800
	v_add3_u32 v0, v185, v210, s8
	ds_read_b128 v[72:75], v0
	ds_read_b128 v[68:71], v0 offset:16
; #define LAS __attribute__((address_space(3)))
; __device__ __forceinline__ unsigned cvt_pk_bf16(float lo, float hi) { unsigned r; asm("v_cvt_pk_bf16_f32 %0, %1, %2" : "=v"(r) : "v"(lo), "v"(hi)); return r; }
; __device__ __forceinline__ float siluf_(float x) { return x * rcpf_(1.f + __expf(-x)); }
;     __device__ __forceinline__ void operator()(const f32x4 (&acc)[2][2][4][2], const Unit& u, int wr, int wc, int fr, int fq) const {
;     ...
;                     for (int m = 0; m < 4; ++m) {
;                         const int l = 128 * ai + 64 * wr + 16 * m + frL;
;                         const float rs = rt[l];
;                         if (m == 0) {
;                             const int B = 2 * ai + wr;
;                             prevA = (f32x4){0.f, 0.f, 0.f, 0.f}; prevB = prevA;
;                             if (B > 0 && frL >= 14) { const LAS float* hp = halo + ((B - 1) * 2 + (frL - 14)) * 128 + fl; prevA = *(const LAS f32x4*)hp; prevB = *(const LAS f32x4*)(hp + 4); }
;                         }
;                         unsigned wv[4];
; #pragma unroll
;                         for (int n = 0; n < 2; ++n) {
;                             const f32x4 w0 = n ? Wb0 : Wa0, w1 = n ? Wb1 : Wa1, w2 = n ? Wb2 : Wa2, bb = n ? Wbb : Wab;
;                             const f32x4 cur = acc[ai][1][m][n] * rs, uu = acc[ai][0][m][n] * rs, prev = n ? prevB : prevA;
;                             float ov[4];
; #pragma unroll
;                             for (int e = 0; e < 4; ++e) {
;                                 const float ce = cur[e], pe = prev[e];
;                                 const float g1 = dpp_mv<0x121>(k15 ? pe : ce), g2 = dpp_mv<0x122>(k14 ? pe : ce);
;                                 const float cv = fmaf(w0[e], g2, fmaf(w1[e], g1, fmaf(w2[e], ce, bb[e])));
;                                 ov[e] = siluf_(cv) * uu[e];
;                             }
;                             wv[2 * n] = cvt_pk_bf16(ov[0], ov[1]); wv[2 * n + 1] = cvt_pk_bf16(ov[2], ov[3]);
;                             if (n) prevB = cur; else prevA = cur;
;                         }
;                         if (ai > 0 || m > 0 || l >= 2) *(v4u*)((unsigned char*)ACT + (ob + (unsigned)((128 * ai + 16 * m) * DFF * 2))) = (v4u){wv[0], wv[1], wv[2], wv[3]};
;                         __builtin_amdgcn_sched_barrier(0);
;                     }
.LBB0_1395:
	s_or_b64 exec, exec, s[0:1]
	s_waitcnt lgkmcnt(0)
	v_pk_mul_f32 v[64:65], v[64:65], v[76:77] op_sel_hi:[1,0]
	v_pk_mul_f32 v[66:67], v[66:67], v[76:77] op_sel_hi:[1,0]
	v_cndmask_b32_e64 v0, v64, v72, s[6:7]
	v_cndmask_b32_e32 v2, v72, v64, vcc
	v_fma_f32 v3, v160, v64, v148
	v_fmac_f32_dpp v3, v0, v156 row_ror:1 row_mask:0xf bank_mask:0xf bound_ctrl:1
	v_fmac_f32_dpp v3, v2, v152 row_ror:2 row_mask:0xf bank_mask:0xf bound_ctrl:1
	v_mul_f32_e32 v0, 0xbfb8aa3b, v3
	v_exp_f32_e32 v0, v0
	v_mov_b32_e32 v2, v60
	v_readlane_b32 s0, v252, 8
	v_readlane_b32 s1, v252, 9
	v_add_f32_e32 v0, 1.0, v0
	v_rcp_f32_e32 v77, v0
	s_nop 0
	v_pk_mul_f32 v[2:3], v[2:3], v[76:77]
	s_nop 0
	v_mul_f32_e32 v0, v2, v3
	v_cndmask_b32_e64 v2, v65, v73, s[6:7]
	v_cndmask_b32_e32 v3, v73, v65, vcc
	s_nop 0
	s_nop 0
	v_mov_b32_dpp v60, v3 row_ror:2 row_mask:0xf bank_mask:0xf bound_ctrl:1
	v_fma_f32 v3, v161, v65, v149
	v_fmac_f32_dpp v3, v2, v157 row_ror:1 row_mask:0xf bank_mask:0xf bound_ctrl:1
	v_fmac_f32_e32 v3, v153, v60
	v_mul_f32_e32 v2, 0xbfb8aa3b, v3
	v_exp_f32_e32 v2, v2
	s_nop 0
	v_add_f32_e32 v2, 1.0, v2
	v_rcp_f32_e32 v77, v2
	v_mov_b32_e32 v2, v61
	v_pk_mul_f32 v[2:3], v[2:3], v[76:77]
	s_nop 0
	v_mul_f32_e32 v60, v2, v3
	v_cndmask_b32_e64 v2, v66, v74, s[6:7]
	v_cndmask_b32_e32 v3, v74, v66, vcc
	v_cvt_pk_bf16_f32 v60, v0, v60
	s_nop 0
	v_mov_b32_dpp v61, v3 row_ror:2 row_mask:0xf bank_mask:0xf bound_ctrl:1
	v_fma_f32 v3, v162, v66, v150
	v_fmac_f32_dpp v3, v2, v158 row_ror:1 row_mask:0xf bank_mask:0xf bound_ctrl:1
	v_fmac_f32_e32 v3, v154, v61
	v_mul_f32_e32 v2, 0xbfb8aa3b, v3
	v_exp_f32_e32 v2, v2
	s_nop 0
	v_add_f32_e32 v2, 1.0, v2
	v_rcp_f32_e32 v77, v2
	v_mov_b32_e32 v2, v62
	v_pk_mul_f32 v[2:3], v[2:3], v[76:77]
	s_nop 0
	v_mul_f32_e32 v61, v2, v3
	v_cndmask_b32_e64 v2, v67, v75, s[6:7]
	v_cndmask_b32_e32 v3, v75, v67, vcc
	s_nop 0
	s_nop 0
	v_mov_b32_dpp v62, v3 row_ror:2 row_mask:0xf bank_mask:0xf bound_ctrl:1
	v_fma_f32 v3, v163, v67, v151
	v_fmac_f32_dpp v3, v2, v159 row_ror:1 row_mask:0xf bank_mask:0xf bound_ctrl:1
	v_fmac_f32_e32 v3, v155, v62
	v_mul_f32_e32 v2, 0xbfb8aa3b, v3
	v_exp_f32_e32 v2, v2
	s_nop 0
	v_add_f32_e32 v2, 1.0, v2
	v_rcp_f32_e32 v77, v2
	v_mov_b32_e32 v2, v63
	v_pk_mul_f32 v[2:3], v[2:3], v[76:77]
	v_pk_mul_f32 v[56:57], v[56:57], v[76:77] op_sel_hi:[1,0]
	v_mul_f32_e32 v2, v2, v3
	v_cndmask_b32_e64 v0, v56, v68, s[6:7]
	v_cvt_pk_bf16_f32 v61, v61, v2
	v_pk_mul_f32 v[2:3], v[58:59], v[76:77] op_sel_hi:[1,0]
	v_cndmask_b32_e32 v58, v68, v56, vcc
	v_fma_f32 v59, v144, v56, v132
	v_fmac_f32_dpp v59, v0, v140 row_ror:1 row_mask:0xf bank_mask:0xf bound_ctrl:1
	v_fmac_f32_dpp v59, v58, v136 row_ror:2 row_mask:0xf bank_mask:0xf bound_ctrl:1
	v_mul_f32_e32 v0, 0xbfb8aa3b, v59
	v_exp_f32_e32 v0, v0
	v_mov_b32_e32 v58, v52
	v_cndmask_b32_e64 v52, v57, v69, s[6:7]
	v_add_f32_e32 v0, 1.0, v0
	v_rcp_f32_e32 v77, v0
	s_nop 0
	v_pk_mul_f32 v[58:59], v[58:59], v[76:77]
	s_nop 0
	v_mul_f32_e32 v0, v58, v59
	v_cndmask_b32_e32 v58, v69, v57, vcc
	v_fma_f32 v59, v145, v57, v133
	v_fmac_f32_dpp v59, v52, v141 row_ror:1 row_mask:0xf bank_mask:0xf bound_ctrl:1
	v_fmac_f32_dpp v59, v58, v137 row_ror:2 row_mask:0xf bank_mask:0xf bound_ctrl:1
	v_mul_f32_e32 v52, 0xbfb8aa3b, v59
	v_exp_f32_e32 v52, v52
	v_mov_b32_e32 v58, v53
	v_add_f32_e32 v52, 1.0, v52
	v_rcp_f32_e32 v77, v52
	s_nop 0
	v_pk_mul_f32 v[52:53], v[58:59], v[76:77]
	s_nop 0
	v_mul_f32_e32 v58, v52, v53
	v_cndmask_b32_e64 v52, v2, v70, s[6:7]
	v_cndmask_b32_e32 v53, v70, v2, vcc
	v_cvt_pk_bf16_f32 v62, v0, v58
	v_add_u32_e32 v0, 0xb0000, v184
	v_mov_b32_dpp v59, v53 row_ror:2 row_mask:0xf bank_mask:0xf bound_ctrl:1
	v_fma_f32 v53, v146, v2, v134
	v_fmac_f32_dpp v53, v52, v142 row_ror:1 row_mask:0xf bank_mask:0xf bound_ctrl:1
	v_fmac_f32_e32 v53, v138, v59
	v_mul_f32_e32 v52, 0xbfb8aa3b, v53
	v_exp_f32_e32 v52, v52
	s_nop 0
	v_add_f32_e32 v52, 1.0, v52
	v_rcp_f32_e32 v77, v52
	v_mov_b32_e32 v52, v54
	v_pk_mul_f32 v[52:53], v[52:53], v[76:77]
	s_nop 0
	v_mul_f32_e32 v54, v52, v53
	v_cndmask_b32_e64 v52, v3, v71, s[6:7]
	v_cndmask_b32_e32 v53, v71, v3, vcc
	s_nop 0
	s_nop 0
	v_mov_b32_dpp v59, v53 row_ror:2 row_mask:0xf bank_mask:0xf bound_ctrl:1
	v_fma_f32 v53, v147, v3, v135
	v_fmac_f32_dpp v53, v52, v143 row_ror:1 row_mask:0xf bank_mask:0xf bound_ctrl:1
	v_fmac_f32_e32 v53, v139, v59
	v_mul_f32_e32 v52, 0xbfb8aa3b, v53
	v_exp_f32_e32 v52, v52
	s_nop 0
	v_add_f32_e32 v52, 1.0, v52
	v_rcp_f32_e32 v77, v52
	v_mov_b32_e32 v52, v55
	v_pk_mul_f32 v[52:53], v[52:53], v[76:77]
	s_nop 0
	v_mul_f32_e32 v52, v52, v53
	v_cvt_pk_bf16_f32 v63, v54, v52
	global_store_dwordx4 v0, v[60:63], s[0:1]
	ds_read_b32 v52, v209 offset:576
	v_mov_b32_e32 v54, v44
	s_waitcnt lgkmcnt(0)
; #define LAS __attribute__((address_space(3)))
; __device__ __forceinline__ unsigned cvt_pk_bf16(float lo, float hi) { unsigned r; asm("v_cvt_pk_bf16_f32 %0, %1, %2" : "=v"(r) : "v"(lo), "v"(hi)); return r; }
; __device__ __forceinline__ float siluf_(float x) { return x * rcpf_(1.f + __expf(-x)); }
;     __device__ __forceinline__ void operator()(const f32x4 (&acc)[2][2][4][2], const Unit& u, int wr, int wc, int fr, int fq) const {
;     ...
;                     for (int m = 0; m < 4; ++m) {
;                         const int l = 128 * ai + 64 * wr + 16 * m + frL;
;                         const float rs = rt[l];
;                         if (m == 0) {
;                             const int B = 2 * ai + wr;
;                             prevA = (f32x4){0.f, 0.f, 0.f, 0.f}; prevB = prevA;
;                             if (B > 0 && frL >= 14) { const LAS float* hp = halo + ((B - 1) * 2 + (frL - 14)) * 128 + fl; prevA = *(const LAS f32x4*)hp; prevB = *(const LAS f32x4*)(hp + 4); }
;                         }
;                         unsigned wv[4];
; #pragma unroll
;                         for (int n = 0; n < 2; ++n) {
;                             const f32x4 w0 = n ? Wb0 : Wa0, w1 = n ? Wb1 : Wa1, w2 = n ? Wb2 : Wa2, bb = n ? Wbb : Wab;
;                             const f32x4 cur = acc[ai][1][m][n] * rs, uu = acc[ai][0][m][n] * rs, prev = n ? prevB : prevA;
;                             float ov[4];
; #pragma unroll
;                             for (int e = 0; e < 4; ++e) {
;                                 const float ce = cur[e], pe = prev[e];
;                                 const float g1 = dpp_mv<0x121>(k15 ? pe : ce), g2 = dpp_mv<0x122>(k14 ? pe : ce);
;                                 const float cv = fmaf(w0[e], g2, fmaf(w1[e], g1, fmaf(w2[e], ce, bb[e])));
;                                 ov[e] = siluf_(cv) * uu[e];
;                             }
;                             wv[2 * n] = cvt_pk_bf16(ov[0], ov[1]); wv[2 * n + 1] = cvt_pk_bf16(ov[2], ov[3]);
;                             if (n) prevB = cur; else prevA = cur;
;                         }
;                         if (ai > 0 || m > 0 || l >= 2) *(v4u*)((unsigned char*)ACT + (ob + (unsigned)((128 * ai + 16 * m) * DFF * 2))) = (v4u){wv[0], wv[1], wv[2], wv[3]};
;                         __builtin_amdgcn_sched_barrier(0);
;                     }
	v_pk_mul_f32 v[48:49], v[48:49], v[52:53] op_sel_hi:[1,0]
	s_nop 0
	v_cndmask_b32_e64 v0, v48, v64, s[6:7]
	v_pk_mul_f32 v[50:51], v[50:51], v[52:53] op_sel_hi:[1,0]
	v_cndmask_b32_e32 v53, v64, v48, vcc
	v_fma_f32 v55, v160, v48, v148
	v_fmac_f32_dpp v55, v0, v156 row_ror:1 row_mask:0xf bank_mask:0xf bound_ctrl:1
	v_fmac_f32_dpp v55, v53, v152 row_ror:2 row_mask:0xf bank_mask:0xf bound_ctrl:1
	v_mul_f32_e32 v0, 0xbfb8aa3b, v55
	v_exp_f32_e32 v0, v0
	v_cndmask_b32_e64 v44, v49, v65, s[6:7]
	v_add_f32_e32 v0, 1.0, v0
	v_rcp_f32_e32 v53, v0
	s_nop 0
	v_pk_mul_f32 v[54:55], v[54:55], v[52:53]
	s_nop 0
	v_mul_f32_e32 v0, v54, v55
	v_cndmask_b32_e32 v53, v65, v49, vcc
	v_fma_f32 v55, v161, v49, v149
	v_fmac_f32_dpp v55, v44, v157 row_ror:1 row_mask:0xf bank_mask:0xf bound_ctrl:1
	v_fmac_f32_dpp v55, v53, v153 row_ror:2 row_mask:0xf bank_mask:0xf bound_ctrl:1
	v_mul_f32_e32 v44, 0xbfb8aa3b, v55
	v_exp_f32_e32 v44, v44
	v_mov_b32_e32 v54, v45
	v_add_f32_e32 v44, 1.0, v44
	v_rcp_f32_e32 v53, v44
	s_nop 0
	v_pk_mul_f32 v[44:45], v[54:55], v[52:53]
	s_nop 0
	v_mul_f32_e32 v54, v44, v45
	v_cndmask_b32_e64 v44, v50, v66, s[6:7]
	v_cndmask_b32_e32 v45, v66, v50, vcc
	s_nop 0
	s_nop 0
	v_mov_b32_dpp v53, v45 row_ror:2 row_mask:0xf bank_mask:0xf bound_ctrl:1
	v_fma_f32 v45, v162, v50, v150
	v_fmac_f32_dpp v45, v44, v158 row_ror:1 row_mask:0xf bank_mask:0xf bound_ctrl:1
	v_fmac_f32_e32 v45, v154, v53
	v_mul_f32_e32 v44, 0xbfb8aa3b, v45
	v_exp_f32_e32 v44, v44
	s_nop 0
	v_add_f32_e32 v44, 1.0, v44
	v_rcp_f32_e32 v53, v44
	v_mov_b32_e32 v44, v46
	v_pk_mul_f32 v[44:45], v[44:45], v[52:53]
	s_nop 0
	v_mul_f32_e32 v46, v44, v45
	v_cndmask_b32_e64 v44, v51, v67, s[6:7]
	v_cndmask_b32_e32 v45, v67, v51, vcc
	s_nop 0
	s_nop 0
	v_mov_b32_dpp v53, v45 row_ror:2 row_mask:0xf bank_mask:0xf bound_ctrl:1
	v_fma_f32 v45, v163, v51, v151
	v_fmac_f32_dpp v45, v44, v159 row_ror:1 row_mask:0xf bank_mask:0xf bound_ctrl:1
	v_fmac_f32_e32 v45, v155, v53
	v_mul_f32_e32 v44, 0xbfb8aa3b, v45
	v_exp_f32_e32 v44, v44
	s_nop 0
	v_add_f32_e32 v44, 1.0, v44
	v_rcp_f32_e32 v53, v44
	v_mov_b32_e32 v44, v47
	v_pk_mul_f32 v[44:45], v[44:45], v[52:53]
	v_pk_mul_f32 v[40:41], v[40:41], v[52:53] op_sel_hi:[1,0]
	v_mul_f32_e32 v45, v44, v45
	v_cvt_pk_bf16_f32 v44, v0, v54
	v_cndmask_b32_e64 v0, v40, v56, s[6:7]
	v_cvt_pk_bf16_f32 v45, v46, v45
	v_cndmask_b32_e32 v46, v56, v40, vcc
	v_fma_f32 v47, v144, v40, v132
	v_fmac_f32_dpp v47, v0, v140 row_ror:1 row_mask:0xf bank_mask:0xf bound_ctrl:1
	v_fmac_f32_dpp v47, v46, v136 row_ror:2 row_mask:0xf bank_mask:0xf bound_ctrl:1
	v_mul_f32_e32 v0, 0xbfb8aa3b, v47
	v_exp_f32_e32 v0, v0
	v_pk_mul_f32 v[42:43], v[42:43], v[52:53] op_sel_hi:[1,0]
	v_mov_b32_e32 v46, v36
	v_cndmask_b32_e64 v36, v41, v57, s[6:7]
	v_add_f32_e32 v0, 1.0, v0
	v_rcp_f32_e32 v53, v0
	s_nop 0
	v_pk_mul_f32 v[46:47], v[46:47], v[52:53]
	s_nop 0
	v_mul_f32_e32 v0, v46, v47
	v_cndmask_b32_e32 v46, v57, v41, vcc
	v_fma_f32 v47, v145, v41, v133
	v_fmac_f32_dpp v47, v36, v141 row_ror:1 row_mask:0xf bank_mask:0xf bound_ctrl:1
	v_fmac_f32_dpp v47, v46, v137 row_ror:2 row_mask:0xf bank_mask:0xf bound_ctrl:1
	v_mul_f32_e32 v36, 0xbfb8aa3b, v47
	v_exp_f32_e32 v36, v36
	v_mov_b32_e32 v46, v37
	v_add_f32_e32 v36, 1.0, v36
	v_rcp_f32_e32 v53, v36
	s_nop 0
	v_pk_mul_f32 v[36:37], v[46:47], v[52:53]
	s_nop 0
	v_mul_f32_e32 v46, v36, v37
	v_cndmask_b32_e64 v36, v42, v2, s[6:7]
	v_cndmask_b32_e32 v2, v2, v42, vcc
	v_fma_f32 v37, v146, v42, v134
	v_fmac_f32_dpp v37, v36, v142 row_ror:1 row_mask:0xf bank_mask:0xf bound_ctrl:1
	v_fmac_f32_dpp v37, v2, v138 row_ror:2 row_mask:0xf bank_mask:0xf bound_ctrl:1
	v_mul_f32_e32 v2, 0xbfb8aa3b, v37
	v_exp_f32_e32 v2, v2
	v_mov_b32_e32 v36, v38
	v_cvt_pk_bf16_f32 v46, v0, v46
	v_add_u32_e32 v0, 0xc6000, v184
	v_add_f32_e32 v2, 1.0, v2
	v_rcp_f32_e32 v53, v2
	v_cndmask_b32_e64 v2, v43, v3, s[6:7]
	v_cndmask_b32_e32 v3, v3, v43, vcc
	v_pk_mul_f32 v[36:37], v[36:37], v[52:53]
	s_nop 0
	v_mul_f32_e32 v36, v36, v37
	v_mov_b32_dpp v37, v3 row_ror:2 row_mask:0xf bank_mask:0xf bound_ctrl:1
	v_fma_f32 v3, v147, v43, v135
	v_fmac_f32_dpp v3, v2, v143 row_ror:1 row_mask:0xf bank_mask:0xf bound_ctrl:1
	v_fmac_f32_e32 v3, v139, v37
	v_mul_f32_e32 v2, 0xbfb8aa3b, v3
	v_exp_f32_e32 v2, v2
	s_nop 0
	v_add_f32_e32 v2, 1.0, v2
	v_rcp_f32_e32 v53, v2
	v_mov_b32_e32 v2, v39
	v_pk_mul_f32 v[2:3], v[2:3], v[52:53]
	s_nop 0
	v_mul_f32_e32 v2, v2, v3
	v_cvt_pk_bf16_f32 v47, v36, v2
	global_store_dwordx4 v0, v[44:47], s[0:1]
	ds_read_b32 v36, v209 offset:640
	s_waitcnt lgkmcnt(0)
; #define LAS __attribute__((address_space(3)))
; __device__ __forceinline__ unsigned cvt_pk_bf16(float lo, float hi) { unsigned r; asm("v_cvt_pk_bf16_f32 %0, %1, %2" : "=v"(r) : "v"(lo), "v"(hi)); return r; }
; __device__ __forceinline__ float siluf_(float x) { return x * rcpf_(1.f + __expf(-x)); }
;     __device__ __forceinline__ void operator()(const f32x4 (&acc)[2][2][4][2], const Unit& u, int wr, int wc, int fr, int fq) const {
;     ...
;                     for (int m = 0; m < 4; ++m) {
;                         const int l = 128 * ai + 64 * wr + 16 * m + frL;
;                         const float rs = rt[l];
;                         if (m == 0) {
;                             const int B = 2 * ai + wr;
;                             prevA = (f32x4){0.f, 0.f, 0.f, 0.f}; prevB = prevA;
;                             if (B > 0 && frL >= 14) { const LAS float* hp = halo + ((B - 1) * 2 + (frL - 14)) * 128 + fl; prevA = *(const LAS f32x4*)hp; prevB = *(const LAS f32x4*)(hp + 4); }
;                         }
;                         unsigned wv[4];
; #pragma unroll
;                         for (int n = 0; n < 2; ++n) {
;                             const f32x4 w0 = n ? Wb0 : Wa0, w1 = n ? Wb1 : Wa1, w2 = n ? Wb2 : Wa2, bb = n ? Wbb : Wab;
;                             const f32x4 cur = acc[ai][1][m][n] * rs, uu = acc[ai][0][m][n] * rs, prev = n ? prevB : prevA;
;                             float ov[4];
; #pragma unroll
;                             for (int e = 0; e < 4; ++e) {
;                                 const float ce = cur[e], pe = prev[e];
;                                 const float g1 = dpp_mv<0x121>(k15 ? pe : ce), g2 = dpp_mv<0x122>(k14 ? pe : ce);
;                                 const float cv = fmaf(w0[e], g2, fmaf(w1[e], g1, fmaf(w2[e], ce, bb[e])));
;                                 ov[e] = siluf_(cv) * uu[e];
;                             }
;                             wv[2 * n] = cvt_pk_bf16(ov[0], ov[1]); wv[2 * n + 1] = cvt_pk_bf16(ov[2], ov[3]);
;                             if (n) prevB = cur; else prevA = cur;
;                         }
;                         if (ai > 0 || m > 0 || l >= 2) *(v4u*)((unsigned char*)ACT + (ob + (unsigned)((128 * ai + 16 * m) * DFF * 2))) = (v4u){wv[0], wv[1], wv[2], wv[3]};
;                         __builtin_amdgcn_sched_barrier(0);
;                     }
	v_pk_mul_f32 v[32:33], v[32:33], v[36:37] op_sel_hi:[1,0]
	s_nop 0
	v_cndmask_b32_e64 v0, v32, v48, s[6:7]
	v_pk_mul_f32 v[2:3], v[34:35], v[36:37] op_sel_hi:[1,0]
	v_cndmask_b32_e32 v34, v48, v32, vcc
	v_fma_f32 v35, v160, v32, v148
	v_fmac_f32_dpp v35, v0, v156 row_ror:1 row_mask:0xf bank_mask:0xf bound_ctrl:1
	v_fmac_f32_dpp v35, v34, v152 row_ror:2 row_mask:0xf bank_mask:0xf bound_ctrl:1
	v_mul_f32_e32 v0, 0xbfb8aa3b, v35
	v_exp_f32_e32 v0, v0
	v_mov_b32_e32 v34, v28
	v_cndmask_b32_e64 v28, v33, v49, s[6:7]
	v_add_f32_e32 v0, 1.0, v0
	v_rcp_f32_e32 v37, v0
	s_nop 0
	v_pk_mul_f32 v[34:35], v[34:35], v[36:37]
	s_nop 0
	v_mul_f32_e32 v0, v34, v35
	v_cndmask_b32_e32 v34, v49, v33, vcc
	v_fma_f32 v35, v161, v33, v149
	v_fmac_f32_dpp v35, v28, v157 row_ror:1 row_mask:0xf bank_mask:0xf bound_ctrl:1
	v_fmac_f32_dpp v35, v34, v153 row_ror:2 row_mask:0xf bank_mask:0xf bound_ctrl:1
	v_mul_f32_e32 v28, 0xbfb8aa3b, v35
	v_exp_f32_e32 v28, v28
	v_mov_b32_e32 v34, v29
	v_add_f32_e32 v28, 1.0, v28
	v_rcp_f32_e32 v37, v28
	s_nop 0
	v_pk_mul_f32 v[28:29], v[34:35], v[36:37]
	s_nop 0
	v_mul_f32_e32 v34, v28, v29
	v_cndmask_b32_e64 v28, v2, v50, s[6:7]
	v_cndmask_b32_e32 v29, v50, v2, vcc
	s_nop 0
	s_nop 0
	v_mov_b32_dpp v35, v29 row_ror:2 row_mask:0xf bank_mask:0xf bound_ctrl:1
	v_fma_f32 v29, v162, v2, v150
	v_fmac_f32_dpp v29, v28, v158 row_ror:1 row_mask:0xf bank_mask:0xf bound_ctrl:1
	v_fmac_f32_e32 v29, v154, v35
	v_mul_f32_e32 v28, 0xbfb8aa3b, v29
	v_exp_f32_e32 v28, v28
	s_nop 0
	v_add_f32_e32 v28, 1.0, v28
	v_rcp_f32_e32 v37, v28
	v_mov_b32_e32 v28, v30
	v_pk_mul_f32 v[28:29], v[28:29], v[36:37]
	s_nop 0
	v_mul_f32_e32 v30, v28, v29
	v_cndmask_b32_e64 v28, v3, v51, s[6:7]
	v_cndmask_b32_e32 v29, v51, v3, vcc
	s_nop 0
	s_nop 0
	v_mov_b32_dpp v35, v29 row_ror:2 row_mask:0xf bank_mask:0xf bound_ctrl:1
	v_fma_f32 v29, v163, v3, v151
	v_fmac_f32_dpp v29, v28, v159 row_ror:1 row_mask:0xf bank_mask:0xf bound_ctrl:1
	v_fmac_f32_e32 v29, v155, v35
	v_mul_f32_e32 v28, 0xbfb8aa3b, v29
	v_exp_f32_e32 v28, v28
	s_nop 0
	v_add_f32_e32 v28, 1.0, v28
	v_rcp_f32_e32 v37, v28
	v_mov_b32_e32 v28, v31
	v_pk_mul_f32 v[28:29], v[28:29], v[36:37]
	v_pk_mul_f32 v[24:25], v[24:25], v[36:37] op_sel_hi:[1,0]
	v_mul_f32_e32 v29, v28, v29
	v_cvt_pk_bf16_f32 v28, v0, v34
	v_cndmask_b32_e64 v0, v24, v40, s[6:7]
	v_cvt_pk_bf16_f32 v29, v30, v29
	v_cndmask_b32_e32 v30, v40, v24, vcc
	v_fma_f32 v31, v144, v24, v132
	v_fmac_f32_dpp v31, v0, v140 row_ror:1 row_mask:0xf bank_mask:0xf bound_ctrl:1
	v_fmac_f32_dpp v31, v30, v136 row_ror:2 row_mask:0xf bank_mask:0xf bound_ctrl:1
	v_mul_f32_e32 v0, 0xbfb8aa3b, v31
	v_exp_f32_e32 v0, v0
	v_pk_mul_f32 v[26:27], v[26:27], v[36:37] op_sel_hi:[1,0]
	v_mov_b32_e32 v30, v20
	v_cndmask_b32_e64 v20, v25, v41, s[6:7]
	v_add_f32_e32 v0, 1.0, v0
	v_rcp_f32_e32 v37, v0
	s_nop 0
	v_pk_mul_f32 v[30:31], v[30:31], v[36:37]
	s_nop 0
	v_mul_f32_e32 v0, v30, v31
	v_cndmask_b32_e32 v30, v41, v25, vcc
	v_fma_f32 v31, v145, v25, v133
	v_fmac_f32_dpp v31, v20, v141 row_ror:1 row_mask:0xf bank_mask:0xf bound_ctrl:1
	v_fmac_f32_dpp v31, v30, v137 row_ror:2 row_mask:0xf bank_mask:0xf bound_ctrl:1
	v_mul_f32_e32 v20, 0xbfb8aa3b, v31
	v_exp_f32_e32 v20, v20
	v_mov_b32_e32 v30, v21
	v_add_f32_e32 v20, 1.0, v20
	v_rcp_f32_e32 v37, v20
	s_nop 0
	v_pk_mul_f32 v[20:21], v[30:31], v[36:37]
	s_nop 0
	v_mul_f32_e32 v30, v20, v21
	v_cndmask_b32_e64 v20, v26, v42, s[6:7]
	v_cndmask_b32_e32 v21, v42, v26, vcc
	v_cvt_pk_bf16_f32 v30, v0, v30
	v_add_u32_e32 v0, 0xdc000, v184
	v_mov_b32_dpp v31, v21 row_ror:2 row_mask:0xf bank_mask:0xf bound_ctrl:1
	v_fma_f32 v21, v146, v26, v134
	v_fmac_f32_dpp v21, v20, v142 row_ror:1 row_mask:0xf bank_mask:0xf bound_ctrl:1
	v_fmac_f32_e32 v21, v138, v31
	v_mul_f32_e32 v20, 0xbfb8aa3b, v21
	v_exp_f32_e32 v20, v20
	s_nop 0
	v_add_f32_e32 v20, 1.0, v20
	v_rcp_f32_e32 v37, v20
	v_mov_b32_e32 v20, v22
	v_pk_mul_f32 v[20:21], v[20:21], v[36:37]
	s_nop 0
	v_mul_f32_e32 v22, v20, v21
	v_cndmask_b32_e64 v20, v27, v43, s[6:7]
	v_cndmask_b32_e32 v21, v43, v27, vcc
	s_nop 0
	s_nop 0
	v_mov_b32_dpp v31, v21 row_ror:2 row_mask:0xf bank_mask:0xf bound_ctrl:1
	v_fma_f32 v21, v147, v27, v135
	v_fmac_f32_dpp v21, v20, v143 row_ror:1 row_mask:0xf bank_mask:0xf bound_ctrl:1
	v_fmac_f32_e32 v21, v139, v31
	v_mul_f32_e32 v20, 0xbfb8aa3b, v21
	v_exp_f32_e32 v20, v20
	s_nop 0
	v_add_f32_e32 v20, 1.0, v20
	v_rcp_f32_e32 v37, v20
	v_mov_b32_e32 v20, v23
	v_pk_mul_f32 v[20:21], v[20:21], v[36:37]
	s_nop 0
	v_mul_f32_e32 v20, v20, v21
	v_cvt_pk_bf16_f32 v31, v22, v20
	global_store_dwordx4 v0, v[28:31], s[0:1]
	ds_read_b32 v20, v209 offset:704
	s_nop 0
	v_mov_b32_e32 v28, v14
	s_waitcnt lgkmcnt(0)
; #define LAS __attribute__((address_space(3)))
; __device__ __forceinline__ unsigned cvt_pk_bf16(float lo, float hi) { unsigned r; asm("v_cvt_pk_bf16_f32 %0, %1, %2" : "=v"(r) : "v"(lo), "v"(hi)); return r; }
; __device__ __forceinline__ float siluf_(float x) { return x * rcpf_(1.f + __expf(-x)); }
;     __device__ __forceinline__ void operator()(const f32x4 (&acc)[2][2][4][2], const Unit& u, int wr, int wc, int fr, int fq) const {
;     ...
;                     for (int m = 0; m < 4; ++m) {
;                         const int l = 128 * ai + 64 * wr + 16 * m + frL;
;                         const float rs = rt[l];
;                         if (m == 0) {
;                             const int B = 2 * ai + wr;
;                             prevA = (f32x4){0.f, 0.f, 0.f, 0.f}; prevB = prevA;
;                             if (B > 0 && frL >= 14) { const LAS float* hp = halo + ((B - 1) * 2 + (frL - 14)) * 128 + fl; prevA = *(const LAS f32x4*)hp; prevB = *(const LAS f32x4*)(hp + 4); }
;                         }
;                         unsigned wv[4];
; #pragma unroll
;                         for (int n = 0; n < 2; ++n) {
;                             const f32x4 w0 = n ? Wb0 : Wa0, w1 = n ? Wb1 : Wa1, w2 = n ? Wb2 : Wa2, bb = n ? Wbb : Wab;
;                             const f32x4 cur = acc[ai][1][m][n] * rs, uu = acc[ai][0][m][n] * rs, prev = n ? prevB : prevA;
;                             float ov[4];
; #pragma unroll
;                             for (int e = 0; e < 4; ++e) {
;                                 const float ce = cur[e], pe = prev[e];
;                                 const float g1 = dpp_mv<0x121>(k15 ? pe : ce), g2 = dpp_mv<0x122>(k14 ? pe : ce);
;                                 const float cv = fmaf(w0[e], g2, fmaf(w1[e], g1, fmaf(w2[e], ce, bb[e])));
;                                 ov[e] = siluf_(cv) * uu[e];
;                             }
;                             wv[2 * n] = cvt_pk_bf16(ov[0], ov[1]); wv[2 * n + 1] = cvt_pk_bf16(ov[2], ov[3]);
;                             if (n) prevB = cur; else prevA = cur;
;                         }
;                         if (ai > 0 || m > 0 || l >= 2) *(v4u*)((unsigned char*)ACT + (ob + (unsigned)((128 * ai + 16 * m) * DFF * 2))) = (v4u){wv[0], wv[1], wv[2], wv[3]};
;                         __builtin_amdgcn_sched_barrier(0);
;                     }
	v_pk_mul_f32 v[16:17], v[16:17], v[20:21] op_sel_hi:[1,0]
	s_nop 0
	v_cndmask_b32_e64 v0, v16, v32, s[6:7]
	v_pk_mul_f32 v[18:19], v[18:19], v[20:21] op_sel_hi:[1,0]
	v_cndmask_b32_e32 v21, v32, v16, vcc
	v_fma_f32 v23, v160, v16, v148
	s_nop 0
	v_mov_b32_dpp v16, v21 row_ror:2 row_mask:0xf bank_mask:0xf bound_ctrl:1
	v_fmac_f32_dpp v23, v0, v156 row_ror:1 row_mask:0xf bank_mask:0xf bound_ctrl:1
	v_fmac_f32_e32 v23, v152, v16
	v_mul_f32_e32 v0, 0xbfb8aa3b, v23
	v_exp_f32_e32 v0, v0
	v_cndmask_b32_e64 v16, v17, v33, s[6:7]
	v_cndmask_b32_e32 v22, v33, v17, vcc
	v_fma_f32 v17, v161, v17, v149
	v_add_f32_e32 v0, 1.0, v0
	v_rcp_f32_e32 v21, v0
	v_fmac_f32_dpp v17, v16, v157 row_ror:1 row_mask:0xf bank_mask:0xf bound_ctrl:1
	v_mov_b32_dpp v0, v22 row_ror:2 row_mask:0xf bank_mask:0xf bound_ctrl:1
	v_fmac_f32_e32 v17, v153, v0
	v_mul_f32_e32 v0, 0xbfb8aa3b, v17
	v_exp_f32_e32 v0, v0
	v_mov_b32_e32 v22, v12
	v_pk_mul_f32 v[22:23], v[22:23], v[20:21]
	v_fma_f32 v29, v162, v18, v150
	v_add_f32_e32 v0, 1.0, v0
	v_rcp_f32_e32 v21, v0
	v_cndmask_b32_e64 v0, v18, v2, s[6:7]
	v_cndmask_b32_e32 v2, v2, v18, vcc
	v_mov_b32_e32 v16, v13
	v_fmac_f32_dpp v29, v0, v158 row_ror:1 row_mask:0xf bank_mask:0xf bound_ctrl:1
	v_fmac_f32_dpp v29, v2, v154 row_ror:2 row_mask:0xf bank_mask:0xf bound_ctrl:1
	v_mul_f32_e32 v0, 0xbfb8aa3b, v29
	v_exp_f32_e32 v0, v0
	v_pk_mul_f32 v[12:13], v[16:17], v[20:21]
	v_cndmask_b32_e32 v2, v3, v19, vcc
	v_fmac_f32_e32 v151, v163, v19
	v_add_f32_e32 v0, 1.0, v0
	v_rcp_f32_e32 v21, v0
	v_cndmask_b32_e64 v0, v19, v3, s[6:7]
	v_mov_b32_dpp v2, v2 row_ror:2 row_mask:0xf bank_mask:0xf bound_ctrl:1
	v_mov_b32_e32 v150, v15
	v_fmac_f32_dpp v151, v0, v159 row_ror:1 row_mask:0xf bank_mask:0xf bound_ctrl:1
	v_fmac_f32_e32 v151, v155, v2
	v_mul_f32_e32 v0, 0xbfb8aa3b, v151
	v_exp_f32_e32 v0, v0
	v_pk_mul_f32 v[2:3], v[28:29], v[20:21]
	v_mul_f32_e32 v16, v22, v23
	v_mul_f32_e32 v14, v2, v3
	v_add_f32_e32 v0, 1.0, v0
	v_rcp_f32_e32 v21, v0
	v_mul_f32_e32 v0, v12, v13
	v_pk_mul_f32 v[2:3], v[8:9], v[20:21] op_sel_hi:[1,0]
	s_nop 0
	v_cndmask_b32_e64 v8, v2, v24, s[6:7]
	v_cndmask_b32_e32 v9, v24, v2, vcc
	v_pk_mul_f32 v[10:11], v[10:11], v[20:21] op_sel_hi:[1,0]
	s_nop 0
	v_mov_b32_dpp v12, v9 row_ror:2 row_mask:0xf bank_mask:0xf bound_ctrl:1
	v_fma_f32 v9, v144, v2, v132
	v_fmac_f32_dpp v9, v8, v140 row_ror:1 row_mask:0xf bank_mask:0xf bound_ctrl:1
	v_fmac_f32_e32 v9, v136, v12
	v_mul_f32_e32 v2, 0xbfb8aa3b, v9
	v_exp_f32_e32 v2, v2
	v_pk_mul_f32 v[12:13], v[150:151], v[20:21]
	v_cndmask_b32_e32 v8, v25, v3, vcc
	v_mul_f32_e32 v12, v12, v13
	v_add_f32_e32 v2, 1.0, v2
	v_rcp_f32_e32 v21, v2
	v_cndmask_b32_e64 v2, v3, v25, s[6:7]
	v_fma_f32 v13, v145, v3, v133
	s_nop 0
	v_fmac_f32_dpp v13, v2, v141 row_ror:1 row_mask:0xf bank_mask:0xf bound_ctrl:1
	v_fmac_f32_dpp v13, v8, v137 row_ror:2 row_mask:0xf bank_mask:0xf bound_ctrl:1
	v_mul_f32_e32 v2, 0xbfb8aa3b, v13
	v_exp_f32_e32 v3, v2
	v_cvt_pk_bf16_f32 v2, v16, v0
	v_mov_b32_e32 v8, v4
	v_pk_mul_f32 v[8:9], v[8:9], v[20:21]
	v_add_f32_e32 v0, 1.0, v3
	v_rcp_f32_e32 v21, v0
	v_cndmask_b32_e64 v0, v10, v26, s[6:7]
	v_cndmask_b32_e32 v3, v26, v10, vcc
	v_fma_f32 v15, v146, v10, v134
	v_fmac_f32_dpp v15, v0, v142 row_ror:1 row_mask:0xf bank_mask:0xf bound_ctrl:1
	v_fmac_f32_dpp v15, v3, v138 row_ror:2 row_mask:0xf bank_mask:0xf bound_ctrl:1
	v_mul_f32_e32 v0, 0xbfb8aa3b, v15
	v_exp_f32_e32 v0, v0
	v_cvt_pk_bf16_f32 v3, v14, v12
	v_mov_b32_e32 v12, v5
	v_pk_mul_f32 v[4:5], v[12:13], v[20:21]
	v_add_f32_e32 v0, 1.0, v0
	v_rcp_f32_e32 v21, v0
	v_cndmask_b32_e64 v0, v11, v27, s[6:7]
	v_cndmask_b32_e32 v10, v27, v11, vcc
	v_fmac_f32_e32 v135, v147, v11
	v_fmac_f32_dpp v135, v0, v143 row_ror:1 row_mask:0xf bank_mask:0xf bound_ctrl:1
	v_fmac_f32_dpp v135, v10, v139 row_ror:2 row_mask:0xf bank_mask:0xf bound_ctrl:1
	v_mul_f32_e32 v0, 0xbfb8aa3b, v135
	v_exp_f32_e32 v0, v0
	v_mov_b32_e32 v14, v6
	v_mul_f32_e32 v10, v8, v9
	v_pk_mul_f32 v[8:9], v[14:15], v[20:21]
	v_add_f32_e32 v0, 1.0, v0
	v_rcp_f32_e32 v21, v0
	v_mov_b32_e32 v134, v7
	v_mul_f32_e32 v0, v4, v5
	v_mul_f32_e32 v6, v8, v9
	v_pk_mul_f32 v[4:5], v[134:135], v[20:21]
	s_nop 0
	v_mul_f32_e32 v5, v4, v5
	v_cvt_pk_bf16_f32 v4, v10, v0
	v_add_u32_e32 v0, 0xf2000, v184
	v_cvt_pk_bf16_f32 v5, v6, v5
	global_store_dwordx4 v0, v[2:5], s[0:1]
	s_and_b64 vcc, exec, s[4:5]
	s_mov_b64 s[0:1], -1
	s_cbranch_vccnz .LBB0_1168
